# gating: 16-byte U loads and MIX stores (lane-half exchange with v_permlane32_swap) instead of four scattered 8-byte accesses each
# speedup vs baseline: 1.0106x; 1.0039x over previous
; __device__ __forceinline__ int tid_fresh() { int t = threadIdx.x; asm volatile("" : "+v"(t)); return t; }
; __device__ __forceinline__ void gate_phase(int bx, int G, bool skip_ctx, const bf16* __restrict__ VG, const bf16* __restrict__ U, const float* __restrict__ stats, ...
;     const int tid = tid_fresh(), wid = tid >> 6, lane = tid & 63, r32 = lane & 31, hi = lane >> 5;
;     bf16* T = (bf16*)lds;
;     const int q = tid >> 2, dc = (tid & 3) * 16;
;     const int db = wid & 1, pb = wid >> 1, p = pb * 32 + r32;
;     const int NU = (M / 128) * 8;
;     auto unit_ok = [&](int u) { return u < NU && !(skip_ctx && ((u >> 3) % 34) < 2); };
;     auto next_unit = [&](int u) { u += G; while (u < NU && !unit_ok(u)) u += G; return u; };
;     int u = bx; if (!unit_ok(u)) u = next_unit(u);
;     GateRegs R;
;     ...
;     if (u < NU) GATE_LOAD(u);
.LBB0_39:
	s_cmpk_gt_i32 s3, 0x87f
	s_cbranch_scc1 .LBB0_51
	s_lshl_b32 s22, s12, 9
	s_ashr_i32 s23, s22, 31
	s_lshl_b64 s[26:27], s[22:23], 2
	s_waitcnt lgkmcnt(0)
	s_add_u32 s22, s8, s26
	s_addc_u32 s23, s9, s27
	s_add_u32 s26, s10, s26
	s_addc_u32 s27, s11, s27
	s_ashr_i32 s13, s12, 31
	s_lshl_b64 s[8:9], s[12:13], 18
	s_add_u32 s8, s28, s8
	s_addc_u32 s9, s29, s9
	s_add_u32 s38, s8, 0x5800000
	s_addc_u32 s39, s9, 0
	s_lshl_b32 s8, s12, 10
	s_ashr_i32 s9, s8, 31
	s_lshl_b64 s[8:9], s[8:9], 2
	s_add_u32 s6, s6, s8
	s_addc_u32 s7, s7, s9
	v_ashrrev_i32_e32 v100, 2, v4
	s_movk_i32 s8, 0xffe0
	v_bfi_b32 v102, s8, v100, v4
	s_add_u32 s8, s28, 0x11efa000
	s_addc_u32 s9, s29, 0
	s_add_u32 s10, s28, 0x140fa000
	s_addc_u32 s11, s29, 0
	s_ashr_i32 s46, s3, 3
	s_ashr_i32 s47, s46, 31
	v_lshlrev_b32_e32 v0, 4, v4
	s_lshl_b64 s[46:47], s[46:47], 7
	v_ashrrev_i32_e32 v101, 31, v100
	v_and_b32_e32 v6, 48, v0
	v_lshl_add_u64 v[0:1], s[46:47], 0, v[100:101]
	s_and_b32 s13, s3, 7
	v_lshlrev_b64 v[2:3], 6, v[0:1]
	v_lshlrev_b64 v[0:1], 10, v[0:1]
	v_lshl_add_u64 v[0:1], s[10:11], 0, v[0:1]
	s_lshl_b32 s72, s13, 7
	v_lshl_add_u64 v[0:1], v[0:1], 0, s[72:73]
	v_lshlrev_b32_e32 v160, 1, v6
	v_lshl_add_u64 v[2:3], s[40:41], 0, v[2:3]
	v_lshl_add_u64 v[0:1], v[0:1], 0, v[160:161]
	v_ashrrev_i32_e32 v103, 31, v102
	global_load_dwordx4 v[16:19], v[2:3], off offset:48
	global_load_dwordx4 v[20:23], v[2:3], off offset:32
	global_load_dwordx4 v[24:27], v[2:3], off offset:16
	global_load_dwordx4 v[28:31], v[2:3], off
	global_load_dwordx4 v[32:35], v[0:1], off offset:16 nt
	global_load_dwordx4 v[36:39], v[0:1], off nt
	v_lshl_add_u64 v[0:1], s[46:47], 0, v[102:103]
	v_lshlrev_b64 v[0:1], 10, v[0:1]
	v_lshrrev_b32_e32 v2, 1, v4
	v_lshl_add_u64 v[0:1], s[8:9], 0, v[0:1]
	v_and_b32_e32 v8, 32, v2
	v_bfe_u32 v5, v4, 5, 1
	v_lshl_add_u64 v[0:1], v[0:1], 0, s[72:73]
	v_lshlrev_b32_e32 v160, 1, v8
	v_lshl_add_u64 v[0:1], v[0:1], 0, v[160:161]
	v_lshlrev_b32_e32 v160, 5, v5
	v_lshl_add_u64 v[0:1], v[0:1], 0, v[160:161]
	global_load_dwordx4 v[126:129], v[0:1], off nt
	global_load_dwordx4 v[130:133], v[0:1], off offset:16 nt
	v_lshl_add_u64 v[0:1], s[72:73], 0, v[102:103]
	v_lshlrev_b64 v[0:1], 8, v[0:1]
	v_lshl_add_u64 v[0:1], s[38:39], 0, v[0:1]
	v_lshlrev_b32_e32 v160, 4, v5
	v_lshl_add_u64 v[10:11], v[0:1], 0, v[160:161]
	global_load_dwordx4 v[0:3], v[10:11], off
	global_load_dwordx4 v[60:63], v[10:11], off offset:32
	global_load_dwordx4 v[64:67], v[10:11], off offset:64
	global_load_dwordx4 v[52:55], v[10:11], off offset:96
	global_load_dwordx4 v[56:59], v[10:11], off offset:128
	global_load_dwordx4 v[48:51], v[10:11], off offset:160
	global_load_dwordx4 v[44:47], v[10:11], off offset:192
	global_load_dwordx4 v[40:43], v[10:11], off offset:224
	v_lshlrev_b32_e32 v10, 4, v5
	v_lshlrev_b32_e32 v12, 2, v6
	v_mov_b32_e32 v13, v161
	v_and_or_b32 v4, v4, 31, v8
	s_movk_i32 s13, 0x110
	v_mul_u32_u24_e32 v9, 0x88, v6
	v_lshl_add_u64 v[104:105], s[22:23], 0, v[12:13]
	v_lshl_add_u64 v[108:109], s[26:27], 0, v[12:13]
	v_lshlrev_b32_e32 v5, 1, v100
	v_mad_u32_u24 v7, v4, s13, 0
	v_or_b32_e32 v4, v10, v8
	v_lshlrev_b64 v[12:13], 11, v[102:103]
	v_lshlrev_b32_e32 v9, 1, v9
	v_lshl_add_u64 v[110:111], s[38:39], 0, v[160:161]
	v_lshl_add_u64 v[112:113], s[16:17], 0, v[12:13]
	v_add3_u32 v134, 0, v5, v9
	v_add3_u32 v135, 0, v9, v5
	v_lshlrev_b32_e32 v114, 1, v6
	v_lshlrev_b32_e32 v116, 1, v8
	v_lshlrev_b32_e32 v118, 1, v10
	v_add_u32_e32 v136, v7, v160
	v_lshlrev_b32_e32 v160, 1, v4
	s_and_b32 s37, s3, 7
	s_lshl_b32 s38, s37, 8
	s_mov_b32 s39, 0
	v_lshl_add_u64 v[252:253], v[104:105], 0, s[38:39]
	global_load_dwordx4 v[218:221], v[252:253], off
	global_load_dwordx4 v[222:225], v[252:253], off offset:16
	global_load_dwordx4 v[226:229], v[252:253], off offset:32
	global_load_dwordx4 v[230:233], v[252:253], off offset:48
	v_lshl_add_u64 v[252:253], v[108:109], 0, s[38:39]
	global_load_dwordx4 v[234:237], v[252:253], off
	global_load_dwordx4 v[238:241], v[252:253], off offset:16
	global_load_dwordx4 v[242:245], v[252:253], off offset:32
	global_load_dwordx4 v[246:249], v[252:253], off offset:48
	v_lshl_add_u32 v252, s37, 7, v102
	v_ashrrev_i32_e32 v253, 31, v252
	v_lshl_add_u64 v[252:253], v[252:253], 2, s[6:7]
	global_load_dword v137, v[252:253], off
	s_waitcnt vmcnt(0)
	v_permlane32_swap_b32_e32 v126, v128
	v_permlane32_swap_b32_e32 v127, v129
	v_permlane32_swap_b32_e32 v130, v132
	v_permlane32_swap_b32_e32 v131, v133
	v_mov_b64_e32 v[124:125], v[126:127]
	v_mov_b64_e32 v[122:123], v[130:131]
	v_mov_b64_e32 v[120:121], v[128:129]
	v_mov_b64_e32 v[106:107], v[132:133]
	s_branch .LBB0_45

; __device__ __forceinline__ unsigned pk2(float lo, float hi) { return pg8::cvt_pk_bf16(lo, hi); }
; __device__ __forceinline__ float bflo(unsigned w) { return __uint_as_float(w << 16); }
; __device__ __forceinline__ float bfhi(unsigned w) { return __uint_as_float(w & 0xffff0000u); }
; __device__ __forceinline__ void gate_phase(int bx, int G, bool skip_ctx, const bf16* __restrict__ VG, const bf16* __restrict__ U, const float* __restrict__ stats, ...
;     ...
;         f32x16 acc = {};
;         const bf16* trow = T + (db * 32 + r32) * GT_PITCH + hi * 8;
; #pragma unroll
;         for (int ks = 0; ks < 8; ++ks) {
;             const bf16x8 av = *(const bf16x8*)(trow + ks * 16);
;             acc = __builtin_amdgcn_mfma_f32_32x32x16_bf16(av, wcur[ks], acc, 0, 0, 0);
;         }
;         const size_t row = (size_t)chunk * 128 + p;
; #pragma unroll
;         for (int g4 = 0; g4 < 4; ++g4) {
;             const int d0 = db * 32 + 8 * g4 + 4 * hi;
;             u32x2 w;
;             w.x = pk2(bflo(ucur[g4].x) * (acc[4 * g4 + 0] + bias), bfhi(ucur[g4].x) * (acc[4 * g4 + 1] + bias));
;             w.y = pk2(bflo(ucur[g4].y) * (acc[4 * g4 + 2] + bias), bfhi(ucur[g4].y) * (acc[4 * g4 + 3] + bias));
;             *(u32x2*)(MIX + row * 1024 + 512 + h * 64 + d0) = w;
;         }
;         __syncthreads();
.LBB0_44:
	s_waitcnt lgkmcnt(0)
	s_barrier
	ds_read_b128 v[4:7], v136
	ds_read_b128 v[138:141], v136 offset:32
	s_waitcnt lgkmcnt(1)
	v_mfma_f32_32x32x16_bf16 v[0:15], v[4:7], v[0:3], 0
	s_ashr_i32 s26, s13, 3
	s_ashr_i32 s27, s26, 31
	s_lshl_b64 s[26:27], s[26:27], 18
	s_lshl_b32 s72, s19, 1
	s_andn2_b64 vcc, exec, s[22:23]
	s_waitcnt lgkmcnt(0)
	v_mfma_f32_32x32x16_bf16 v[0:15], v[138:141], v[60:63], v[0:15]
	ds_read_b128 v[60:63], v136 offset:64
	s_waitcnt lgkmcnt(0)
	v_mfma_f32_32x32x16_bf16 v[0:15], v[60:63], v[64:67], v[0:15]
	ds_read_b128 v[60:63], v136 offset:96
	v_mov_b64_e32 v[64:65], v[76:77]
	v_mov_b64_e32 v[66:67], v[78:79]
	s_waitcnt lgkmcnt(0)
	v_mfma_f32_32x32x16_bf16 v[0:15], v[60:63], v[52:55], v[0:15]
	ds_read_b128 v[52:55], v136 offset:128
	v_mov_b64_e32 v[60:61], v[72:73]
	v_mov_b64_e32 v[62:63], v[74:75]
	s_waitcnt lgkmcnt(0)
	v_mfma_f32_32x32x16_bf16 v[0:15], v[52:55], v[56:59], v[0:15]
	ds_read_b128 v[52:55], v136 offset:160
	v_mov_b64_e32 v[56:57], v[84:85]
	v_mov_b64_e32 v[58:59], v[86:87]
	s_waitcnt lgkmcnt(0)
	v_mfma_f32_32x32x16_bf16 v[0:15], v[52:55], v[48:51], v[0:15]
	ds_read_b128 v[48:51], v136 offset:192
	v_mov_b64_e32 v[52:53], v[80:81]
	v_mov_b64_e32 v[54:55], v[82:83]
	s_waitcnt lgkmcnt(0)
	v_mfma_f32_32x32x16_bf16 v[0:15], v[48:51], v[44:47], v[0:15]
	ds_read_b128 v[44:47], v136 offset:224
	v_mov_b64_e32 v[48:49], v[88:89]
	v_mov_b64_e32 v[50:51], v[90:91]
	s_waitcnt lgkmcnt(0)
	v_mfma_f32_32x32x16_bf16 v[0:15], v[44:47], v[40:43], v[0:15]
	v_lshlrev_b32_e32 v42, 16, v124
	v_lshl_add_u64 v[40:41], v[112:113], 0, s[26:27]
	v_lshl_add_u64 v[40:41], v[40:41], 0, s[72:73]
	v_mov_b64_e32 v[44:45], v[92:93]
	v_mov_b64_e32 v[46:47], v[94:95]
	s_nop 10
	v_add_f32_e32 v0, v137, v0
	v_mul_f32_e32 v0, v0, v42
	v_and_b32_e32 v42, 0xffff0000, v124
	v_add_f32_e32 v1, v137, v1
	v_mul_f32_e32 v1, v1, v42
	v_cvt_pk_bf16_f32 v172, v0, v1
	v_lshlrev_b32_e32 v0, 16, v125
	v_add_f32_e32 v1, v137, v2
	v_mul_f32_e32 v0, v1, v0
	v_and_b32_e32 v1, 0xffff0000, v125
	v_add_f32_e32 v2, v137, v3
	v_mul_f32_e32 v1, v2, v1
	v_lshlrev_b32_e32 v2, 16, v122
	v_add_f32_e32 v3, v137, v4
	v_mul_f32_e32 v2, v3, v2
	v_and_b32_e32 v3, 0xffff0000, v122
	v_add_f32_e32 v4, v137, v5
	v_cvt_pk_bf16_f32 v173, v0, v1
	v_lshl_add_u64 v[0:1], v[40:41], 0, v[160:161]
	v_mul_f32_e32 v3, v4, v3
	v_cvt_pk_bf16_f32 v176, v2, v3
	v_lshlrev_b32_e32 v3, 16, v123
	v_add_f32_e32 v4, v137, v6
	v_mul_f32_e32 v3, v4, v3
	v_and_b32_e32 v4, 0xffff0000, v123
	v_add_f32_e32 v5, v137, v7
	v_mul_f32_e32 v4, v5, v4
	v_cvt_pk_bf16_f32 v177, v3, v4
	v_lshlrev_b32_e32 v2, 16, v120
	v_add_f32_e32 v3, v137, v8
	v_mul_f32_e32 v2, v3, v2
	v_and_b32_e32 v3, 0xffff0000, v120
	v_add_f32_e32 v4, v137, v9
	v_mul_f32_e32 v3, v4, v3
	v_cvt_pk_bf16_f32 v174, v2, v3
	v_lshlrev_b32_e32 v3, 16, v121
	v_add_f32_e32 v4, v137, v10
	v_mul_f32_e32 v3, v4, v3
	v_and_b32_e32 v4, 0xffff0000, v121
	v_add_f32_e32 v5, v137, v11
	v_mul_f32_e32 v4, v5, v4
	v_cvt_pk_bf16_f32 v175, v3, v4
	v_lshlrev_b32_e32 v2, 16, v106
	v_add_f32_e32 v3, v137, v12
	v_mul_f32_e32 v2, v3, v2
	v_and_b32_e32 v3, 0xffff0000, v106
	v_add_f32_e32 v4, v137, v13
	v_mul_f32_e32 v3, v4, v3
	v_cvt_pk_bf16_f32 v178, v2, v3
	v_lshlrev_b32_e32 v3, 16, v107
	v_add_f32_e32 v4, v137, v14
	v_mul_f32_e32 v3, v4, v3
	v_and_b32_e32 v4, 0xffff0000, v107
	v_add_f32_e32 v5, v137, v15
	v_mul_f32_e32 v4, v5, v4
	v_cvt_pk_bf16_f32 v179, v3, v4
	s_nop 1
	v_permlane32_swap_b32_e32 v172, v174
	v_permlane32_swap_b32_e32 v173, v175
	v_permlane32_swap_b32_e32 v176, v178
	v_permlane32_swap_b32_e32 v177, v179
	global_store_dwordx4 v[0:1], v[172:175], off offset:1024
	global_store_dwordx4 v[0:1], v[176:179], off offset:1040
	s_waitcnt vmcnt(2)
	v_permlane32_swap_b32_e32 v126, v128
	v_permlane32_swap_b32_e32 v127, v129
	v_permlane32_swap_b32_e32 v130, v132
	v_permlane32_swap_b32_e32 v131, v133
	v_mov_b64_e32 v[0:1], v[68:69]
	v_mov_b64_e32 v[40:41], v[96:97]
	v_mov_b64_e32 v[124:125], v[126:127]
	v_mov_b64_e32 v[122:123], v[130:131]
	v_mov_b64_e32 v[120:121], v[128:129]
	v_mov_b64_e32 v[106:107], v[132:133]
	v_mov_b64_e32 v[2:3], v[70:71]
	v_mov_b64_e32 v[42:43], v[98:99]
	s_barrier
	s_cbranch_vccnz .LBB0_51

; __device__ __forceinline__ void gate_phase(int bx, int G, bool skip_ctx, const bf16* __restrict__ VG, const bf16* __restrict__ U, const float* __restrict__ stats, ...
;     ...
;         const int un = next_unit(u);
;         if (un < NU) GATE_LOAD(un);
.LBB0_49:
	v_mov_b64_e32 v[70:71], v[2:3]
	v_mov_b64_e32 v[74:75], v[62:63]
	v_mov_b64_e32 v[78:79], v[66:67]
	v_mov_b64_e32 v[82:83], v[54:55]
	v_mov_b64_e32 v[86:87], v[58:59]
	v_mov_b64_e32 v[90:91], v[50:51]
	v_mov_b64_e32 v[94:95], v[46:47]
	v_mov_b64_e32 v[98:99], v[42:43]
	s_mov_b64 s[22:23], 0
	s_andn2_b64 vcc, exec, s[38:39]
	v_mov_b64_e32 v[126:127], v[124:125]
	v_mov_b64_e32 v[128:129], v[122:123]
	v_mov_b64_e32 v[130:131], v[120:121]
	v_mov_b64_e32 v[132:133], v[106:107]
	v_mov_b64_e32 v[68:69], v[0:1]
	v_mov_b64_e32 v[72:73], v[60:61]
	v_mov_b64_e32 v[76:77], v[64:65]
	v_mov_b64_e32 v[80:81], v[52:53]
	v_mov_b64_e32 v[84:85], v[56:57]
	v_mov_b64_e32 v[88:89], v[48:49]
	v_mov_b64_e32 v[92:93], v[44:45]
	v_mov_b64_e32 v[96:97], v[40:41]
	s_cbranch_vccz .LBB0_44
	s_ashr_i32 s27, s26, 31
	s_lshl_b64 s[22:23], s[26:27], 7
	v_lshl_add_u64 v[4:5], s[22:23], 0, v[100:101]
	s_and_b32 s25, s3, 7
	v_lshlrev_b64 v[6:7], 6, v[4:5]
	v_lshlrev_b64 v[4:5], 10, v[4:5]
	v_lshl_add_u64 v[4:5], s[10:11], 0, v[4:5]
	s_lshl_b32 s72, s25, 7
	v_lshl_add_u64 v[4:5], v[4:5], 0, s[72:73]
	v_mov_b32_e32 v115, v161
	v_lshl_add_u64 v[6:7], s[40:41], 0, v[6:7]
	v_lshl_add_u64 v[4:5], v[4:5], 0, v[114:115]
	global_load_dwordx4 v[16:19], v[6:7], off offset:48
	global_load_dwordx4 v[20:23], v[6:7], off offset:32
	global_load_dwordx4 v[24:27], v[6:7], off offset:16
	global_load_dwordx4 v[28:31], v[6:7], off
	global_load_dwordx4 v[32:35], v[4:5], off offset:16 nt
	global_load_dwordx4 v[36:39], v[4:5], off nt
	v_lshl_add_u64 v[4:5], s[22:23], 0, v[102:103]
	v_lshlrev_b64 v[4:5], 10, v[4:5]
	v_lshl_add_u64 v[4:5], s[8:9], 0, v[4:5]
	v_lshl_add_u64 v[4:5], v[4:5], 0, s[72:73]
	v_mov_b32_e32 v117, v161
	v_lshl_add_u64 v[4:5], v[4:5], 0, v[116:117]
	v_mov_b32_e32 v119, v161
	v_lshl_add_u64 v[4:5], v[4:5], 0, v[118:119]
	global_load_dwordx4 v[126:129], v[4:5], off nt
	global_load_dwordx4 v[130:133], v[4:5], off offset:16 nt
	v_lshl_add_u64 v[4:5], s[72:73], 0, v[102:103]
	v_lshlrev_b64 v[4:5], 8, v[4:5]
	v_lshl_add_u64 v[4:5], v[110:111], 0, v[4:5]
	s_mov_b64 s[22:23], -1
	s_branch .LBB0_44
